# stagalate
# speedup vs baseline: 1.0008x; 1.0008x over previous
.Lsrt_loop:
	s_waitcnt vmcnt(4)
	ds_write_b128 v57, v[46:49]
	ds_write_b128 v57, v[42:45] offset:16
	ds_write_b128 v57, v[38:41] offset:20480
	ds_write_b128 v57, v[34:37] offset:20496
	ds_read_b128 v[176:179], v59 offset:61440
	ds_read_b128 v[180:183], v58 offset:40960
	ds_read_b128 v[184:187], v59 offset:64000
	ds_read_b128 v[188:191], v58 offset:43520
	ds_read_b128 v[192:195], v58 offset:46080
	ds_read_b128 v[196:199], v58 offset:48640
	ds_read_b128 v[200:203], v59 offset:61504
	ds_read_b128 v[204:207], v58 offset:41024
	ds_read_b128 v[208:211], v59 offset:64064
	ds_read_b128 v[224:227], v58 offset:43584
	ds_read_b128 v[228:231], v58 offset:46144
	ds_read_b128 v[232:235], v58 offset:48704
	s_add_i32 s14, s6, 4
	s_add_i32 s22, s64, -1
	s_min_u32 s14, s14, s22
	s_lshl_b32 s22, s14, 7
	s_waitcnt lgkmcnt(12)
	v_lshl_add_u64 v[124:125], v[50:51], 0, s[22:23]
	v_lshl_add_u64 v[126:127], v[52:53], 0, s[22:23]
	global_load_dwordx4 v[46:49], v[124:125], off
	global_load_dwordx4 v[42:45], v[124:125], off offset:16
	global_load_dwordx4 v[38:41], v[126:127], off
	global_load_dwordx4 v[34:37], v[126:127], off offset:16
	v_mfma_f32_16x16x32_bf16 v[30:33], v[60:63], v[64:67], v[30:33]
	v_mfma_f32_16x16x32_bf16 v[14:17], v[68:71], v[64:67], v[14:17]
	v_mfma_f32_16x16x32_bf16 v[26:29], v[60:63], v[88:91], v[26:29]
	v_mfma_f32_16x16x32_bf16 v[10:13], v[68:71], v[88:91], v[10:13]
	v_mfma_f32_16x16x32_bf16 v[22:25], v[60:63], v[92:95], v[22:25]
	v_mfma_f32_16x16x32_bf16 v[6:9], v[68:71], v[92:95], v[6:9]
	v_mfma_f32_16x16x32_bf16 v[18:21], v[60:63], v[96:99], v[18:21]
	v_mfma_f32_16x16x32_bf16 v[2:5], v[68:71], v[96:99], v[2:5]
	v_mfma_f32_16x16x32_bf16 v[30:33], v[100:103], v[104:107], v[30:33]
	v_mfma_f32_16x16x32_bf16 v[14:17], v[108:111], v[104:107], v[14:17]
	v_mfma_f32_16x16x32_bf16 v[26:29], v[100:103], v[112:115], v[26:29]
	v_mfma_f32_16x16x32_bf16 v[10:13], v[108:111], v[112:115], v[10:13]
	v_mfma_f32_16x16x32_bf16 v[22:25], v[100:103], v[116:119], v[22:25]
	v_mfma_f32_16x16x32_bf16 v[6:9], v[108:111], v[116:119], v[6:9]
	v_mfma_f32_16x16x32_bf16 v[18:21], v[100:103], v[120:123], v[18:21]
	v_mfma_f32_16x16x32_bf16 v[2:5], v[108:111], v[120:123], v[2:5]
	s_waitcnt lgkmcnt(0)
	s_barrier
	s_waitcnt vmcnt(4)
	ds_write_b128 v57, v[84:87] offset:40960
	ds_write_b128 v57, v[80:83] offset:40976
	ds_write_b128 v57, v[76:79] offset:61440
	ds_write_b128 v57, v[72:75] offset:61456
	ds_read_b128 v[60:63], v59 offset:20480
	ds_read_b128 v[64:67], v58
	ds_read_b128 v[68:71], v59 offset:23040
	ds_read_b128 v[88:91], v58 offset:2560
	ds_read_b128 v[92:95], v58 offset:5120
	ds_read_b128 v[96:99], v58 offset:7680
	ds_read_b128 v[100:103], v59 offset:20544
	ds_read_b128 v[104:107], v58 offset:64
	ds_read_b128 v[108:111], v59 offset:23104
	ds_read_b128 v[112:115], v58 offset:2624
	ds_read_b128 v[116:119], v58 offset:5184
	ds_read_b128 v[120:123], v58 offset:7744
	s_add_i32 s14, s6, 5
	s_add_i32 s22, s64, -1
	s_min_u32 s14, s14, s22
	s_lshl_b32 s22, s14, 7
	s_waitcnt lgkmcnt(12)
	v_lshl_add_u64 v[124:125], v[50:51], 0, s[22:23]
	v_lshl_add_u64 v[126:127], v[52:53], 0, s[22:23]
	global_load_dwordx4 v[84:87], v[124:125], off
	global_load_dwordx4 v[80:83], v[124:125], off offset:16
	global_load_dwordx4 v[76:79], v[126:127], off
	global_load_dwordx4 v[72:75], v[126:127], off offset:16
	v_mfma_f32_16x16x32_bf16 v[30:33], v[176:179], v[180:183], v[30:33]
	v_mfma_f32_16x16x32_bf16 v[14:17], v[184:187], v[180:183], v[14:17]
	v_mfma_f32_16x16x32_bf16 v[26:29], v[176:179], v[188:191], v[26:29]
	v_mfma_f32_16x16x32_bf16 v[10:13], v[184:187], v[188:191], v[10:13]
	v_mfma_f32_16x16x32_bf16 v[22:25], v[176:179], v[192:195], v[22:25]
	v_mfma_f32_16x16x32_bf16 v[6:9], v[184:187], v[192:195], v[6:9]
	v_mfma_f32_16x16x32_bf16 v[18:21], v[176:179], v[196:199], v[18:21]
	v_mfma_f32_16x16x32_bf16 v[2:5], v[184:187], v[196:199], v[2:5]
	v_mfma_f32_16x16x32_bf16 v[30:33], v[200:203], v[204:207], v[30:33]
	v_mfma_f32_16x16x32_bf16 v[14:17], v[208:211], v[204:207], v[14:17]
	v_mfma_f32_16x16x32_bf16 v[26:29], v[200:203], v[224:227], v[26:29]
	v_mfma_f32_16x16x32_bf16 v[10:13], v[208:211], v[224:227], v[10:13]
	v_mfma_f32_16x16x32_bf16 v[22:25], v[200:203], v[228:231], v[22:25]
	v_mfma_f32_16x16x32_bf16 v[6:9], v[208:211], v[228:231], v[6:9]
	v_mfma_f32_16x16x32_bf16 v[18:21], v[200:203], v[232:235], v[18:21]
	v_mfma_f32_16x16x32_bf16 v[2:5], v[208:211], v[232:235], v[2:5]
	s_waitcnt lgkmcnt(0)
	s_barrier
	s_add_i32 s6, s6, 2
	s_cmp_lt_u32 s6, s64
	s_cbranch_scc1 .Lsrt_loop
	s_branch .Lsrt_done
